# h9 + attention output rows stored as 16-byte pieces (lane/lane^32 halves exchanged with v_permlane32_swap) in DA and dilated epilogues
# speedup vs baseline: 1.0099x; 1.0099x over previous
; __device__ __forceinline__ float shx(float v, int m, int lane) { return __int_as_float(__builtin_amdgcn_ds_bpermute((lane ^ m) << 2, __float_as_int(v))); }
; template <int MODE> ...
;     ...
;         if (mp == 1) {
; #pragma unroll
;             for (int dvb = 0; dvb < NDV; ++dvb)
; #pragma unroll
;                 for (int r = 0; r < 16; ++r) { const int dv = 32 * dvb + (r & 3) + 8 * (r >> 2) + 4 * hi; xch[(wq * 128 + dv) * 32 + r32] = acc[dvb][r] * inv; }
;         }
;         __syncthreads();
;         if (mp == 0) {
;             float ss = 0.f;
; #pragma unroll
;             for (int dvb = 0; dvb < NDV; ++dvb)
; #pragma unroll
;                 for (int r = 0; r < 16; ++r) { const int dv = 32 * dvb + (r & 3) + 8 * (r >> 2) + 4 * hi; const float o = acc[dvb][r] * inv - lam * xch[(wq * 128 + dv) * 32 + r32]; acc[dvb][r] = o; ss += o * o; }
;             ss += shx(ss, 32, lane);
;             const float rs = rsqrtf(ss * (1.0f / 128.0f) + RMS_EPS) * one_m_li;
.LBB0_399:
	s_andn2_b64 vcc, exec, s[14:15]
	s_waitcnt lgkmcnt(0)
	s_barrier
	s_cbranch_vccnz .LBB0_401
	s_lshl_b32 s14, s19, 14
	v_add3_u32 v0, v15, v0, s14
	v_add_u32_e32 v15, 0x400, v0
	ds_read2_b32 v[152:153], v0 offset1:32
	ds_read2_b32 v[154:155], v0 offset0:64 offset1:96
	ds_read2_b32 v[156:157], v15 offset1:32
	ds_read2_b32 v[158:159], v15 offset0:64 offset1:96
	v_add_u32_e32 v15, 0x800, v0
	ds_read2_b32 v[160:161], v15 offset1:32
	ds_read2_b32 v[162:163], v15 offset0:64 offset1:96
	v_add_u32_e32 v15, 0xc00, v0
	ds_read2_b32 v[204:205], v15 offset1:32
	ds_read2_b32 v[164:165], v15 offset0:64 offset1:96
	v_add_u32_e32 v15, 0x1000, v0
	ds_read2_b32 v[198:199], v15 offset1:32
	ds_read2_b32 v[202:203], v15 offset0:64 offset1:96
	v_add_u32_e32 v15, 0x1400, v0
	ds_read2_b32 v[192:193], v15 offset1:32
	ds_read2_b32 v[196:197], v15 offset0:64 offset1:96
	v_add_u32_e32 v15, 0x1800, v0
	ds_read2_b32 v[188:189], v15 offset1:32
	ds_read2_b32 v[190:191], v15 offset0:64 offset1:96
	v_add_u32_e32 v15, 0x1c00, v0
	ds_read2_b32 v[184:185], v15 offset1:32
	ds_read2_b32 v[186:187], v15 offset0:64 offset1:96
	v_add_u32_e32 v15, 0x2000, v0
	ds_read2_b32 v[180:181], v15 offset1:32
	ds_read2_b32 v[182:183], v15 offset0:64 offset1:96
	v_add_u32_e32 v15, 0x2400, v0
	ds_read2_b32 v[176:177], v15 offset1:32
	ds_read2_b32 v[178:179], v15 offset0:64 offset1:96
	v_add_u32_e32 v15, 0x2800, v0
	ds_read2_b32 v[172:173], v15 offset1:32
	ds_read2_b32 v[174:175], v15 offset0:64 offset1:96
	v_add_u32_e32 v15, 0x2c00, v0
	ds_read2_b32 v[168:169], v15 offset1:32
	ds_read2_b32 v[170:171], v15 offset0:64 offset1:96
	v_add_u32_e32 v15, 0x3000, v0
	v_lshlrev_b64 v[134:135], 11, v[134:135]
	ds_read2_b32 v[150:151], v15 offset1:32
	ds_read2_b32 v[166:167], v15 offset0:64 offset1:96
	v_add_u32_e32 v15, 0x3400, v0
	v_lshl_add_u64 v[134:135], s[76:77], 0, v[134:135]
	s_lshl_b32 s14, s18, 1
	s_mov_b32 s15, s81
	ds_read2_b32 v[144:145], v15 offset1:32
	ds_read2_b32 v[148:149], v15 offset0:64 offset1:96
	v_add_u32_e32 v15, 0x3800, v0
	v_lshl_add_u64 v[208:209], v[134:135], 0, s[14:15]
	s_waitcnt lgkmcnt(14)
	v_pk_mul_f32 v[134:135], v[132:133], v[154:155]
	v_add_u32_e32 v0, 0x3c00, v0
	v_pk_fma_f32 v[66:67], v[66:67], v[14:15], v[134:135] op_sel_hi:[1,0,1] neg_lo:[0,0,1] neg_hi:[0,0,1]
	v_pk_mul_f32 v[134:135], v[132:133], v[152:153]
	ds_read2_b32 v[138:139], v15 offset1:32
	ds_read2_b32 v[140:141], v15 offset0:64 offset1:96
	ds_read2_b32 v[136:137], v0 offset1:32
	ds_read2_b32 v[142:143], v0 offset0:64 offset1:96
	v_lshlrev_b32_e32 v0, 2, v194
	v_pk_fma_f32 v[134:135], v[64:65], v[14:15], v[134:135] op_sel_hi:[1,0,1] neg_lo:[0,0,1] neg_hi:[0,0,1]
	v_xor_b32_e32 v210, 0x80, v0
	v_pk_mul_f32 v[200:201], v[134:135], v[134:135]
	v_lshlrev_b32_e32 v0, 2, v217
	v_pk_mul_f32 v[152:153], v[132:133], v[158:159]
	v_pk_mul_f32 v[194:195], v[66:67], v[66:67]
	v_lshl_add_u64 v[64:65], v[208:209], 0, v[0:1]
	v_pk_fma_f32 v[70:71], v[70:71], v[14:15], v[152:153] op_sel_hi:[1,0,1] neg_lo:[0,0,1] neg_hi:[0,0,1]
	v_pk_mul_f32 v[152:153], v[132:133], v[156:157]
	v_add_f32_e32 v0, v200, v201
	v_pk_fma_f32 v[152:153], v[68:69], v[14:15], v[152:153] op_sel_hi:[1,0,1] neg_lo:[0,0,1] neg_hi:[0,0,1]
	v_add_f32_e32 v0, v0, v194
	v_pk_mul_f32 v[156:157], v[152:153], v[152:153]
	v_add_f32_e32 v0, v0, v195
	v_pk_mul_f32 v[68:69], v[132:133], v[162:163]
	v_add_f32_e32 v0, v0, v156
	v_pk_mul_f32 v[154:155], v[70:71], v[70:71]
	v_pk_fma_f32 v[68:69], v[74:75], v[14:15], v[68:69] op_sel_hi:[1,0,1] neg_lo:[0,0,1] neg_hi:[0,0,1]
	v_pk_mul_f32 v[74:75], v[132:133], v[160:161]
	v_add_f32_e32 v0, v0, v157
	v_pk_fma_f32 v[74:75], v[72:73], v[14:15], v[74:75] op_sel_hi:[1,0,1] neg_lo:[0,0,1] neg_hi:[0,0,1]
	v_add_f32_e32 v0, v0, v154
	v_pk_mul_f32 v[160:161], v[74:75], v[74:75]
	v_add_f32_e32 v0, v0, v155
	v_pk_mul_f32 v[72:73], v[132:133], v[164:165]
	v_add_f32_e32 v0, v0, v160
	v_pk_mul_f32 v[158:159], v[68:69], v[68:69]
	v_pk_fma_f32 v[72:73], v[78:79], v[14:15], v[72:73] op_sel_hi:[1,0,1] neg_lo:[0,0,1] neg_hi:[0,0,1]
	v_pk_mul_f32 v[78:79], v[132:133], v[204:205]
	v_add_f32_e32 v0, v0, v161
	v_pk_fma_f32 v[76:77], v[76:77], v[14:15], v[78:79] op_sel_hi:[1,0,1] neg_lo:[0,0,1] neg_hi:[0,0,1]
	v_add_f32_e32 v0, v0, v158
	v_pk_mul_f32 v[164:165], v[76:77], v[76:77]
	v_add_f32_e32 v0, v0, v159
	v_pk_mul_f32 v[78:79], v[132:133], v[202:203]
	v_add_f32_e32 v0, v0, v164
	v_pk_mul_f32 v[162:163], v[72:73], v[72:73]
	v_pk_fma_f32 v[50:51], v[50:51], v[14:15], v[78:79] op_sel_hi:[1,0,1] neg_lo:[0,0,1] neg_hi:[0,0,1]
	v_pk_mul_f32 v[78:79], v[132:133], v[198:199]
	v_add_f32_e32 v0, v0, v165
	v_pk_fma_f32 v[78:79], v[48:49], v[14:15], v[78:79] op_sel_hi:[1,0,1] neg_lo:[0,0,1] neg_hi:[0,0,1]
	v_add_f32_e32 v0, v0, v162
	v_pk_mul_f32 v[198:199], v[78:79], v[78:79]
	v_add_f32_e32 v0, v0, v163
	v_pk_mul_f32 v[48:49], v[132:133], v[196:197]
	v_add_f32_e32 v0, v0, v198
	v_pk_mul_f32 v[202:203], v[50:51], v[50:51]
	v_pk_fma_f32 v[48:49], v[54:55], v[14:15], v[48:49] op_sel_hi:[1,0,1] neg_lo:[0,0,1] neg_hi:[0,0,1]
	v_pk_mul_f32 v[54:55], v[132:133], v[192:193]
	v_add_f32_e32 v0, v0, v199
	v_pk_fma_f32 v[54:55], v[52:53], v[14:15], v[54:55] op_sel_hi:[1,0,1] neg_lo:[0,0,1] neg_hi:[0,0,1]
	v_add_f32_e32 v0, v0, v202
	v_pk_mul_f32 v[192:193], v[54:55], v[54:55]
	v_add_f32_e32 v0, v0, v203
	v_pk_mul_f32 v[52:53], v[132:133], v[190:191]
	v_add_f32_e32 v0, v0, v192
	v_pk_mul_f32 v[196:197], v[48:49], v[48:49]
	v_pk_fma_f32 v[52:53], v[58:59], v[14:15], v[52:53] op_sel_hi:[1,0,1] neg_lo:[0,0,1] neg_hi:[0,0,1]
	v_pk_mul_f32 v[58:59], v[132:133], v[188:189]
	v_add_f32_e32 v0, v0, v193
	v_pk_fma_f32 v[58:59], v[56:57], v[14:15], v[58:59] op_sel_hi:[1,0,1] neg_lo:[0,0,1] neg_hi:[0,0,1]
	v_add_f32_e32 v0, v0, v196
	v_pk_mul_f32 v[188:189], v[58:59], v[58:59]
	v_add_f32_e32 v0, v0, v197
	s_waitcnt lgkmcnt(14)
; __device__ __forceinline__ float shx(float v, int m, int lane) { return __int_as_float(__builtin_amdgcn_ds_bpermute((lane ^ m) << 2, __float_as_int(v))); }
; template <int MODE> ...
;     ...
;             float ss = 0.f;
; #pragma unroll
;             for (int dvb = 0; dvb < NDV; ++dvb)
; #pragma unroll
;                 for (int r = 0; r < 16; ++r) { const int dv = 32 * dvb + (r & 3) + 8 * (r >> 2) + 4 * hi; const float o = acc[dvb][r] * inv - lam * xch[(wq * 128 + dv) * 32 + r32]; acc[dvb][r] = o; ss += o * o; }
;             ss += shx(ss, 32, lane);
;             const float rs = rsqrtf(ss * (1.0f / 128.0f) + RMS_EPS) * one_m_li;
	v_pk_mul_f32 v[56:57], v[132:133], v[186:187]
	v_add_f32_e32 v0, v0, v188
	v_pk_mul_f32 v[190:191], v[52:53], v[52:53]
	v_pk_fma_f32 v[56:57], v[62:63], v[14:15], v[56:57] op_sel_hi:[1,0,1] neg_lo:[0,0,1] neg_hi:[0,0,1]
	v_pk_mul_f32 v[62:63], v[132:133], v[184:185]
	v_add_f32_e32 v0, v0, v189
	v_pk_fma_f32 v[60:61], v[60:61], v[14:15], v[62:63] op_sel_hi:[1,0,1] neg_lo:[0,0,1] neg_hi:[0,0,1]
	v_add_f32_e32 v0, v0, v190
	v_pk_mul_f32 v[184:185], v[60:61], v[60:61]
	v_add_f32_e32 v0, v0, v191
	v_pk_mul_f32 v[62:63], v[132:133], v[182:183]
	v_add_f32_e32 v0, v0, v184
	v_pk_mul_f32 v[186:187], v[56:57], v[56:57]
	v_pk_fma_f32 v[34:35], v[34:35], v[14:15], v[62:63] op_sel_hi:[1,0,1] neg_lo:[0,0,1] neg_hi:[0,0,1]
	v_pk_mul_f32 v[62:63], v[132:133], v[180:181]
	v_add_f32_e32 v0, v0, v185
	v_pk_fma_f32 v[62:63], v[32:33], v[14:15], v[62:63] op_sel_hi:[1,0,1] neg_lo:[0,0,1] neg_hi:[0,0,1]
	v_add_f32_e32 v0, v0, v186
	v_pk_mul_f32 v[180:181], v[62:63], v[62:63]
	v_add_f32_e32 v0, v0, v187
	s_waitcnt lgkmcnt(12)
	v_pk_mul_f32 v[32:33], v[132:133], v[178:179]
	v_add_f32_e32 v0, v0, v180
	v_pk_mul_f32 v[182:183], v[34:35], v[34:35]
	v_pk_fma_f32 v[32:33], v[38:39], v[14:15], v[32:33] op_sel_hi:[1,0,1] neg_lo:[0,0,1] neg_hi:[0,0,1]
	v_pk_mul_f32 v[38:39], v[132:133], v[176:177]
	v_add_f32_e32 v0, v0, v181
	v_pk_fma_f32 v[38:39], v[36:37], v[14:15], v[38:39] op_sel_hi:[1,0,1] neg_lo:[0,0,1] neg_hi:[0,0,1]
	v_add_f32_e32 v0, v0, v182
	v_pk_mul_f32 v[176:177], v[38:39], v[38:39]
	v_add_f32_e32 v0, v0, v183
	s_waitcnt lgkmcnt(10)
	v_pk_mul_f32 v[36:37], v[132:133], v[174:175]
	v_add_f32_e32 v0, v0, v176
	v_pk_mul_f32 v[178:179], v[32:33], v[32:33]
	v_pk_fma_f32 v[36:37], v[42:43], v[14:15], v[36:37] op_sel_hi:[1,0,1] neg_lo:[0,0,1] neg_hi:[0,0,1]
	v_pk_mul_f32 v[42:43], v[132:133], v[172:173]
	v_add_f32_e32 v0, v0, v177
	v_pk_fma_f32 v[42:43], v[40:41], v[14:15], v[42:43] op_sel_hi:[1,0,1] neg_lo:[0,0,1] neg_hi:[0,0,1]
	v_add_f32_e32 v0, v0, v178
	v_pk_mul_f32 v[172:173], v[42:43], v[42:43]
	v_add_f32_e32 v0, v0, v179
	v_add_f32_e32 v0, v0, v172
	v_pk_mul_f32 v[174:175], v[36:37], v[36:37]
	s_waitcnt lgkmcnt(9)
	v_pk_mul_f32 v[168:169], v[132:133], v[168:169]
	v_add_f32_e32 v0, v0, v173
	v_pk_fma_f32 v[44:45], v[44:45], v[14:15], v[168:169] op_sel_hi:[1,0,1] neg_lo:[0,0,1] neg_hi:[0,0,1]
	v_add_f32_e32 v0, v0, v174
	s_waitcnt lgkmcnt(8)
	v_pk_mul_f32 v[40:41], v[132:133], v[170:171]
	v_pk_mul_f32 v[168:169], v[44:45], v[44:45]
	v_add_f32_e32 v0, v0, v175
	v_pk_fma_f32 v[40:41], v[46:47], v[14:15], v[40:41] op_sel_hi:[1,0,1] neg_lo:[0,0,1] neg_hi:[0,0,1]
	v_add_f32_e32 v0, v0, v168
	v_pk_mul_f32 v[46:47], v[40:41], v[40:41]
	s_waitcnt lgkmcnt(7)
	v_pk_mul_f32 v[150:151], v[132:133], v[150:151]
	v_add_f32_e32 v0, v0, v169
	v_pk_fma_f32 v[150:151], v[16:17], v[14:15], v[150:151] op_sel_hi:[1,0,1] neg_lo:[0,0,1] neg_hi:[0,0,1]
	v_add_f32_e32 v0, v0, v46
	s_waitcnt lgkmcnt(6)
	v_pk_mul_f32 v[166:167], v[132:133], v[166:167]
	v_pk_mul_f32 v[170:171], v[150:151], v[150:151]
	v_add_f32_e32 v0, v0, v47
	v_pk_fma_f32 v[18:19], v[18:19], v[14:15], v[166:167] op_sel_hi:[1,0,1] neg_lo:[0,0,1] neg_hi:[0,0,1]
	v_add_f32_e32 v0, v0, v170
	v_pk_mul_f32 v[166:167], v[18:19], v[18:19]
	s_waitcnt lgkmcnt(5)
	v_pk_mul_f32 v[144:145], v[132:133], v[144:145]
	v_add_f32_e32 v0, v0, v171
	v_pk_fma_f32 v[20:21], v[20:21], v[14:15], v[144:145] op_sel_hi:[1,0,1] neg_lo:[0,0,1] neg_hi:[0,0,1]
	v_add_f32_e32 v0, v0, v166
	s_waitcnt lgkmcnt(4)
	v_pk_mul_f32 v[16:17], v[132:133], v[148:149]
	v_pk_mul_f32 v[144:145], v[20:21], v[20:21]
	v_add_f32_e32 v0, v0, v167
	v_pk_fma_f32 v[16:17], v[22:23], v[14:15], v[16:17] op_sel_hi:[1,0,1] neg_lo:[0,0,1] neg_hi:[0,0,1]
	v_add_f32_e32 v0, v0, v144
	s_waitcnt lgkmcnt(1)
	v_pk_mul_f32 v[136:137], v[132:133], v[136:137]
	s_waitcnt lgkmcnt(0)
	v_pk_mul_f32 v[142:143], v[132:133], v[142:143]
	v_pk_mul_f32 v[22:23], v[16:17], v[16:17]
	v_pk_mul_f32 v[140:141], v[132:133], v[140:141]
	v_pk_mul_f32 v[138:139], v[132:133], v[138:139]
	v_add_f32_e32 v0, v0, v145
	v_pk_fma_f32 v[28:29], v[28:29], v[14:15], v[136:137] op_sel_hi:[1,0,1] neg_lo:[0,0,1] neg_hi:[0,0,1]
	v_pk_fma_f32 v[30:31], v[30:31], v[14:15], v[142:143] op_sel_hi:[1,0,1] neg_lo:[0,0,1] neg_hi:[0,0,1]
	v_pk_fma_f32 v[26:27], v[26:27], v[14:15], v[140:141] op_sel_hi:[1,0,1] neg_lo:[0,0,1] neg_hi:[0,0,1]
	v_pk_fma_f32 v[14:15], v[24:25], v[14:15], v[138:139] op_sel_hi:[1,0,1] neg_lo:[0,0,1] neg_hi:[0,0,1]
	v_add_f32_e32 v0, v0, v22
	v_pk_mul_f32 v[24:25], v[14:15], v[14:15]
	v_add_f32_e32 v0, v0, v23
	v_add_f32_e32 v0, v0, v24
	v_pk_mul_f32 v[140:141], v[26:27], v[26:27]
	v_add_f32_e32 v0, v0, v25
	v_add_f32_e32 v0, v0, v140
	v_pk_mul_f32 v[136:137], v[28:29], v[28:29]
	v_add_f32_e32 v0, v0, v141
	v_add_f32_e32 v0, v0, v136
	v_pk_mul_f32 v[142:143], v[30:31], v[30:31]
	v_add_f32_e32 v0, v0, v137
	v_add_f32_e32 v0, v0, v142
	v_add_f32_e32 v0, v0, v143
	ds_bpermute_b32 v22, v210, v0
	s_waitcnt lgkmcnt(0)
	v_add_f32_e32 v0, v0, v22
	v_fmamk_f32 v0, v0, 0x3c000000, v207
	v_cmp_gt_f32_e32 vcc, s87, v0
	v_mul_f32_e32 v22, 0x4b800000, v0
	s_nop 0
	v_cndmask_b32_e32 v0, v0, v22, vcc
	v_rsq_f32_e32 v0, v0
	s_nop 0
	v_mul_f32_e32 v22, 0x45800000, v0
	v_cndmask_b32_e32 v0, v0, v22, vcc
	v_mul_f32_e32 v0, v216, v0
	v_pk_mul_f32 v[22:23], v[134:135], v[0:1] op_sel_hi:[1,0]
	v_pk_mul_f32 v[24:25], v[66:67], v[0:1] op_sel_hi:[1,0]
	s_waitcnt vmcnt(15)
; __device__ __forceinline__ unsigned cvt_pk_bf16(float lo, float hi) { f32x2_t v = {lo, hi}; bf16x2_t b = __builtin_convertvector(v, bf16x2_t); return __builtin_bit_cast(unsigned, b); }
; template <int MODE> ...
;     ...
;             bf16* orow = AO + qtok * 1024 + hp * 128;
; #pragma unroll
;             for (int dvb = 0; dvb < NDV; ++dvb)
; #pragma unroll
;                 for (int g4 = 0; g4 < 4; ++g4) { const int dv0 = 32 * dvb + 8 * g4 + 4 * hi; const f32x4 sg = sgv[dvb][g4];
;                     u32x2 w; w.x = cvt_pk_bf16(acc[dvb][4 * g4 + 0] * rs * sg[0], acc[dvb][4 * g4 + 1] * rs * sg[1]); w.y = cvt_pk_bf16(acc[dvb][4 * g4 + 2] * rs * sg[2], acc[dvb][4 * g4 + 3] * rs * sg[3]);
;                     *(u32x2*)(orow + dv0) = w; }
	v_pk_mul_f32 v[22:23], v[128:129], v[22:23]
	v_pk_mul_f32 v[24:25], v[130:131], v[24:25]
	v_cvt_pk_bf16_f32 v218, v22, v23
	v_cvt_pk_bf16_f32 v219, v24, v25
	v_pk_mul_f32 v[22:23], v[152:153], v[0:1] op_sel_hi:[1,0]
	v_pk_mul_f32 v[24:25], v[70:71], v[0:1] op_sel_hi:[1,0]
	s_waitcnt vmcnt(0)
	v_pk_mul_f32 v[22:23], v[124:125], v[22:23]
	v_pk_mul_f32 v[24:25], v[126:127], v[24:25]
	v_cvt_pk_bf16_f32 v220, v22, v23
	v_cvt_pk_bf16_f32 v221, v24, v25
	s_nop 1
	v_permlane32_swap_b32_e32 v218, v220
	v_permlane32_swap_b32_e32 v219, v221
	global_store_dwordx4 v[64:65], v[218:221], off
	v_pk_mul_f32 v[22:23], v[74:75], v[0:1] op_sel_hi:[1,0]
	v_pk_mul_f32 v[24:25], v[68:69], v[0:1] op_sel_hi:[1,0]
	v_pk_mul_f32 v[22:23], v[120:121], v[22:23]
	v_pk_mul_f32 v[24:25], v[122:123], v[24:25]
	v_cvt_pk_bf16_f32 v222, v22, v23
	v_cvt_pk_bf16_f32 v223, v24, v25
	v_pk_mul_f32 v[22:23], v[76:77], v[0:1] op_sel_hi:[1,0]
	v_pk_mul_f32 v[24:25], v[72:73], v[0:1] op_sel_hi:[1,0]
	v_pk_mul_f32 v[22:23], v[116:117], v[22:23]
	v_pk_mul_f32 v[24:25], v[118:119], v[24:25]
	v_cvt_pk_bf16_f32 v224, v22, v23
	v_cvt_pk_bf16_f32 v225, v24, v25
	s_nop 1
	v_permlane32_swap_b32_e32 v222, v224
	v_permlane32_swap_b32_e32 v223, v225
	global_store_dwordx4 v[64:65], v[222:225], off offset:32
	v_pk_mul_f32 v[22:23], v[78:79], v[0:1] op_sel_hi:[1,0]
	v_pk_mul_f32 v[24:25], v[50:51], v[0:1] op_sel_hi:[1,0]
	v_pk_mul_f32 v[22:23], v[112:113], v[22:23]
	v_pk_mul_f32 v[24:25], v[114:115], v[24:25]
	v_cvt_pk_bf16_f32 v242, v22, v23
	v_cvt_pk_bf16_f32 v243, v24, v25
	v_pk_mul_f32 v[22:23], v[54:55], v[0:1] op_sel_hi:[1,0]
	v_pk_mul_f32 v[24:25], v[48:49], v[0:1] op_sel_hi:[1,0]
	v_pk_mul_f32 v[22:23], v[108:109], v[22:23]
	v_pk_mul_f32 v[24:25], v[110:111], v[24:25]
	v_cvt_pk_bf16_f32 v244, v22, v23
	v_cvt_pk_bf16_f32 v245, v24, v25
	s_nop 1
	v_permlane32_swap_b32_e32 v242, v244
	v_permlane32_swap_b32_e32 v243, v245
	global_store_dwordx4 v[64:65], v[242:245], off offset:64
	v_pk_mul_f32 v[22:23], v[58:59], v[0:1] op_sel_hi:[1,0]
	v_pk_mul_f32 v[24:25], v[52:53], v[0:1] op_sel_hi:[1,0]
	v_pk_mul_f32 v[22:23], v[104:105], v[22:23]
	v_pk_mul_f32 v[24:25], v[106:107], v[24:25]
	v_cvt_pk_bf16_f32 v246, v22, v23
	v_cvt_pk_bf16_f32 v247, v24, v25
	v_pk_mul_f32 v[22:23], v[60:61], v[0:1] op_sel_hi:[1,0]
	v_pk_mul_f32 v[24:25], v[56:57], v[0:1] op_sel_hi:[1,0]
	v_pk_mul_f32 v[22:23], v[100:101], v[22:23]
	v_pk_mul_f32 v[24:25], v[102:103], v[24:25]
	v_cvt_pk_bf16_f32 v248, v22, v23
	v_cvt_pk_bf16_f32 v249, v24, v25
	s_nop 1
	v_permlane32_swap_b32_e32 v246, v248
	v_permlane32_swap_b32_e32 v247, v249
	global_store_dwordx4 v[64:65], v[246:249], off offset:96
	v_pk_mul_f32 v[22:23], v[62:63], v[0:1] op_sel_hi:[1,0]
	v_pk_mul_f32 v[24:25], v[34:35], v[0:1] op_sel_hi:[1,0]
	v_pk_mul_f32 v[22:23], v[96:97], v[22:23]
	v_pk_mul_f32 v[24:25], v[98:99], v[24:25]
	v_cvt_pk_bf16_f32 v218, v22, v23
	v_cvt_pk_bf16_f32 v219, v24, v25
	v_pk_mul_f32 v[22:23], v[38:39], v[0:1] op_sel_hi:[1,0]
	v_pk_mul_f32 v[24:25], v[32:33], v[0:1] op_sel_hi:[1,0]
	v_pk_mul_f32 v[22:23], v[92:93], v[22:23]
	v_pk_mul_f32 v[24:25], v[94:95], v[24:25]
	v_cvt_pk_bf16_f32 v220, v22, v23
	v_cvt_pk_bf16_f32 v221, v24, v25
	s_nop 1
	v_permlane32_swap_b32_e32 v218, v220
	v_permlane32_swap_b32_e32 v219, v221
	global_store_dwordx4 v[64:65], v[218:221], off offset:128
	v_pk_mul_f32 v[22:23], v[42:43], v[0:1] op_sel_hi:[1,0]
	v_pk_mul_f32 v[24:25], v[36:37], v[0:1] op_sel_hi:[1,0]
	v_pk_mul_f32 v[22:23], v[88:89], v[22:23]
	v_pk_mul_f32 v[24:25], v[90:91], v[24:25]
	v_cvt_pk_bf16_f32 v222, v22, v23
	v_cvt_pk_bf16_f32 v223, v24, v25
	v_pk_mul_f32 v[22:23], v[44:45], v[0:1] op_sel_hi:[1,0]
	v_pk_mul_f32 v[24:25], v[40:41], v[0:1] op_sel_hi:[1,0]
	v_pk_mul_f32 v[22:23], v[84:85], v[22:23]
	v_pk_mul_f32 v[24:25], v[86:87], v[24:25]
	v_cvt_pk_bf16_f32 v224, v22, v23
	v_cvt_pk_bf16_f32 v225, v24, v25
	s_nop 1
	v_permlane32_swap_b32_e32 v222, v224
	v_permlane32_swap_b32_e32 v223, v225
	global_store_dwordx4 v[64:65], v[222:225], off offset:160
	v_pk_mul_f32 v[22:23], v[150:151], v[0:1] op_sel_hi:[1,0]
	v_pk_mul_f32 v[18:19], v[18:19], v[0:1] op_sel_hi:[1,0]
	v_pk_mul_f32 v[22:23], v[80:81], v[22:23]
	v_pk_mul_f32 v[18:19], v[82:83], v[18:19]
	v_cvt_pk_bf16_f32 v242, v22, v23
	v_cvt_pk_bf16_f32 v243, v18, v19
	v_pk_mul_f32 v[18:19], v[20:21], v[0:1] op_sel_hi:[1,0]
	v_pk_mul_f32 v[16:17], v[16:17], v[0:1] op_sel_hi:[1,0]
	v_pk_mul_f32 v[10:11], v[10:11], v[18:19]
	v_pk_mul_f32 v[12:13], v[12:13], v[16:17]
	v_cvt_pk_bf16_f32 v244, v10, v11
	v_cvt_pk_bf16_f32 v245, v12, v13
	v_pk_mul_f32 v[10:11], v[14:15], v[0:1] op_sel_hi:[1,0]
	s_nop 1
	v_permlane32_swap_b32_e32 v242, v244
	v_permlane32_swap_b32_e32 v243, v245
	global_store_dwordx4 v[64:65], v[242:245], off offset:192
	v_pk_mul_f32 v[6:7], v[6:7], v[10:11]
	v_pk_mul_f32 v[10:11], v[26:27], v[0:1] op_sel_hi:[1,0]
	v_cvt_pk_bf16_f32 v246, v6, v7
	v_pk_mul_f32 v[8:9], v[8:9], v[10:11]
	s_nop 0
	v_cvt_pk_bf16_f32 v247, v8, v9
	v_pk_mul_f32 v[6:7], v[28:29], v[0:1] op_sel_hi:[1,0]
	s_nop 0
	v_pk_mul_f32 v[2:3], v[2:3], v[6:7]
	v_pk_mul_f32 v[6:7], v[30:31], v[0:1] op_sel_hi:[1,0]
	v_cvt_pk_bf16_f32 v248, v2, v3
	v_pk_mul_f32 v[4:5], v[4:5], v[6:7]
	s_nop 0
	v_cvt_pk_bf16_f32 v249, v4, v5
	s_nop 1
	v_permlane32_swap_b32_e32 v246, v248
	v_permlane32_swap_b32_e32 v247, v249
	global_store_dwordx4 v[64:65], v[246:249], off offset:224

; __device__ __forceinline__ float shx(float v, int m, int lane) { return __int_as_float(__builtin_amdgcn_ds_bpermute((lane ^ m) << 2, __float_as_int(v))); }
; template <int MODE> ...
;     ...
;         if (mp == 1) {
; #pragma unroll
;             for (int dvb = 0; dvb < NDV; ++dvb)
; #pragma unroll
;                 for (int r = 0; r < 16; ++r) { const int dv = 32 * dvb + (r & 3) + 8 * (r >> 2) + 4 * hi; xch[(wq * 128 + dv) * 32 + r32] = acc[dvb][r] * inv; }
;         }
;         __syncthreads();
;         if (mp == 0) {
;             float ss = 0.f;
; #pragma unroll
;             for (int dvb = 0; dvb < NDV; ++dvb)
; #pragma unroll
;                 for (int r = 0; r < 16; ++r) { const int dv = 32 * dvb + (r & 3) + 8 * (r >> 2) + 4 * hi; const float o = acc[dvb][r] * inv - lam * xch[(wq * 128 + dv) * 32 + r32]; acc[dvb][r] = o; ss += o * o; }
;             ss += shx(ss, 32, lane);
;             const float rs = rsqrtf(ss * (1.0f / 128.0f) + RMS_EPS) * one_m_li;
.LBB0_420:
	s_andn2_b64 vcc, exec, s[0:1]
	s_waitcnt lgkmcnt(0)
	s_barrier
	s_cbranch_vccnz .LBB0_377
	s_lshl_b32 s0, s4, 14
	v_add3_u32 v136, v15, v14, s0
	v_add_u32_e32 v14, 0x400, v136
	ds_read2_b32 v[154:155], v136 offset1:32
	ds_read2_b32 v[156:157], v136 offset0:64 offset1:96
	ds_read2_b32 v[158:159], v14 offset1:32
	ds_read2_b32 v[160:161], v14 offset0:64 offset1:96
	v_add_u32_e32 v14, 0x800, v136
	ds_read2_b32 v[162:163], v14 offset1:32
	ds_read2_b32 v[164:165], v14 offset0:64 offset1:96
	v_add_u32_e32 v14, 0xc00, v136
	ds_read2_b32 v[174:175], v14 offset1:32
	ds_read2_b32 v[176:177], v14 offset0:64 offset1:96
	v_add_u32_e32 v14, 0x1000, v136
	ds_read2_b32 v[178:179], v14 offset1:32
	ds_read2_b32 v[180:181], v14 offset0:64 offset1:96
	v_add_u32_e32 v14, 0x1400, v136
	ds_read2_b32 v[182:183], v14 offset1:32
	ds_read2_b32 v[184:185], v14 offset0:64 offset1:96
	v_add_u32_e32 v14, 0x1800, v136
	ds_read2_b32 v[186:187], v14 offset1:32
	ds_read2_b32 v[188:189], v14 offset0:64 offset1:96
	v_add_u32_e32 v14, 0x1c00, v136
	ds_read2_b32 v[192:193], v14 offset1:32
	ds_read2_b32 v[194:195], v14 offset0:64 offset1:96
	v_add_u32_e32 v14, 0x2000, v136
	ds_read2_b32 v[196:197], v14 offset1:32
	ds_read2_b32 v[198:199], v14 offset0:64 offset1:96
	v_add_u32_e32 v14, 0x2400, v136
	ds_read2_b32 v[200:201], v14 offset1:32
	ds_read2_b32 v[202:203], v14 offset0:64 offset1:96
	v_add_u32_e32 v14, 0x2800, v136
	ds_read2_b32 v[170:171], v14 offset1:32
	ds_read2_b32 v[204:205], v14 offset0:64 offset1:96
	v_add_u32_e32 v14, 0x2c00, v136
	ds_read2_b32 v[166:167], v14 offset1:32
	ds_read2_b32 v[168:169], v14 offset0:64 offset1:96
	v_add_u32_e32 v14, 0x3000, v136
	ds_read2_b32 v[148:149], v14 offset1:32
	ds_read2_b32 v[152:153], v14 offset0:64 offset1:96
	v_add_u32_e32 v14, 0x3400, v136
	v_add_u32_e32 v137, 0x3c00, v136
	ds_read2_b32 v[142:143], v14 offset1:32
	ds_read2_b32 v[144:145], v14 offset0:64 offset1:96
	ds_read2_b32 v[14:15], v137 offset1:32
	v_add_u32_e32 v136, 0x3800, v136
	ds_read2_b32 v[140:141], v136 offset1:32
	ds_read2_b32 v[138:139], v137 offset0:64 offset1:96
	ds_read2_b32 v[150:151], v136 offset0:64 offset1:96
	s_waitcnt lgkmcnt(11)
	v_pk_mul_f32 v[170:171], v[132:133], v[170:171]
	s_waitcnt lgkmcnt(8)
	v_pk_mul_f32 v[168:169], v[132:133], v[168:169]
	s_waitcnt lgkmcnt(3)
	v_pk_mul_f32 v[14:15], v[132:133], v[14:15]
	v_pk_mul_f32 v[166:167], v[132:133], v[166:167]
	v_pk_fma_f32 v[14:15], v[28:29], v[0:1], v[14:15] op_sel_hi:[1,0,1] neg_lo:[0,0,1] neg_hi:[0,0,1]
	s_waitcnt lgkmcnt(1)
	v_pk_mul_f32 v[28:29], v[132:133], v[138:139]
	v_pk_mul_f32 v[152:153], v[132:133], v[152:153]
	v_pk_fma_f32 v[28:29], v[30:31], v[0:1], v[28:29] op_sel_hi:[1,0,1] neg_lo:[0,0,1] neg_hi:[0,0,1]
	v_lshlrev_b32_e32 v30, 2, v191
	v_xor_b32_e32 v191, 0x80, v30
	v_pk_mul_f32 v[30:31], v[132:133], v[156:157]
	v_pk_mul_f32 v[148:149], v[132:133], v[148:149]
	v_pk_fma_f32 v[30:31], v[66:67], v[0:1], v[30:31] op_sel_hi:[1,0,1] neg_lo:[0,0,1] neg_hi:[0,0,1]
	v_pk_mul_f32 v[66:67], v[132:133], v[154:155]
	v_pk_mul_f32 v[144:145], v[132:133], v[144:145]
	v_pk_fma_f32 v[64:65], v[64:65], v[0:1], v[66:67] op_sel_hi:[1,0,1] neg_lo:[0,0,1] neg_hi:[0,0,1]
	v_pk_mul_f32 v[66:67], v[132:133], v[160:161]
	v_pk_mul_f32 v[154:155], v[64:65], v[64:65]
	v_pk_fma_f32 v[66:67], v[70:71], v[0:1], v[66:67] op_sel_hi:[1,0,1] neg_lo:[0,0,1] neg_hi:[0,0,1]
	v_pk_mul_f32 v[70:71], v[132:133], v[158:159]
	v_pk_mul_f32 v[142:143], v[132:133], v[142:143]
	v_pk_fma_f32 v[70:71], v[68:69], v[0:1], v[70:71] op_sel_hi:[1,0,1] neg_lo:[0,0,1] neg_hi:[0,0,1]
	v_pk_mul_f32 v[68:69], v[132:133], v[164:165]
	s_waitcnt lgkmcnt(0)
	v_pk_mul_f32 v[150:151], v[132:133], v[150:151]
	v_pk_fma_f32 v[68:69], v[74:75], v[0:1], v[68:69] op_sel_hi:[1,0,1] neg_lo:[0,0,1] neg_hi:[0,0,1]
	v_pk_mul_f32 v[74:75], v[132:133], v[162:163]
	v_pk_mul_f32 v[140:141], v[132:133], v[140:141]
	v_pk_fma_f32 v[74:75], v[72:73], v[0:1], v[74:75] op_sel_hi:[1,0,1] neg_lo:[0,0,1] neg_hi:[0,0,1]
	v_pk_mul_f32 v[72:73], v[132:133], v[176:177]
	v_pk_mul_f32 v[172:173], v[30:31], v[30:31]
	v_pk_fma_f32 v[72:73], v[78:79], v[0:1], v[72:73] op_sel_hi:[1,0,1] neg_lo:[0,0,1] neg_hi:[0,0,1]
	v_pk_mul_f32 v[78:79], v[132:133], v[174:175]
	v_pk_fma_f32 v[40:41], v[40:41], v[0:1], v[170:171] op_sel_hi:[1,0,1] neg_lo:[0,0,1] neg_hi:[0,0,1]
	v_pk_fma_f32 v[76:77], v[76:77], v[0:1], v[78:79] op_sel_hi:[1,0,1] neg_lo:[0,0,1] neg_hi:[0,0,1]
	v_pk_mul_f32 v[78:79], v[132:133], v[180:181]
	v_pk_fma_f32 v[46:47], v[46:47], v[0:1], v[168:169] op_sel_hi:[1,0,1] neg_lo:[0,0,1] neg_hi:[0,0,1]
	v_pk_fma_f32 v[50:51], v[50:51], v[0:1], v[78:79] op_sel_hi:[1,0,1] neg_lo:[0,0,1] neg_hi:[0,0,1]
	v_pk_mul_f32 v[78:79], v[132:133], v[178:179]
	v_pk_fma_f32 v[44:45], v[44:45], v[0:1], v[166:167] op_sel_hi:[1,0,1] neg_lo:[0,0,1] neg_hi:[0,0,1]
	v_pk_fma_f32 v[78:79], v[48:49], v[0:1], v[78:79] op_sel_hi:[1,0,1] neg_lo:[0,0,1] neg_hi:[0,0,1]
	v_pk_mul_f32 v[48:49], v[132:133], v[184:185]
	v_pk_fma_f32 v[18:19], v[18:19], v[0:1], v[152:153] op_sel_hi:[1,0,1] neg_lo:[0,0,1] neg_hi:[0,0,1]
	v_pk_fma_f32 v[48:49], v[54:55], v[0:1], v[48:49] op_sel_hi:[1,0,1] neg_lo:[0,0,1] neg_hi:[0,0,1]
	v_pk_mul_f32 v[54:55], v[132:133], v[182:183]
	v_pk_fma_f32 v[16:17], v[16:17], v[0:1], v[148:149] op_sel_hi:[1,0,1] neg_lo:[0,0,1] neg_hi:[0,0,1]
	v_pk_fma_f32 v[54:55], v[52:53], v[0:1], v[54:55] op_sel_hi:[1,0,1] neg_lo:[0,0,1] neg_hi:[0,0,1]
	v_pk_mul_f32 v[52:53], v[132:133], v[188:189]
	v_pk_fma_f32 v[22:23], v[22:23], v[0:1], v[144:145] op_sel_hi:[1,0,1] neg_lo:[0,0,1] neg_hi:[0,0,1]
	v_pk_fma_f32 v[52:53], v[58:59], v[0:1], v[52:53] op_sel_hi:[1,0,1] neg_lo:[0,0,1] neg_hi:[0,0,1]
; __device__ __forceinline__ float shx(float v, int m, int lane) { return __int_as_float(__builtin_amdgcn_ds_bpermute((lane ^ m) << 2, __float_as_int(v))); }
; template <int MODE> ...
;     ...
;             float ss = 0.f;
; #pragma unroll
;             for (int dvb = 0; dvb < NDV; ++dvb)
; #pragma unroll
;                 for (int r = 0; r < 16; ++r) { const int dv = 32 * dvb + (r & 3) + 8 * (r >> 2) + 4 * hi; const float o = acc[dvb][r] * inv - lam * xch[(wq * 128 + dv) * 32 + r32]; acc[dvb][r] = o; ss += o * o; }
;             ss += shx(ss, 32, lane);
;             const float rs = rsqrtf(ss * (1.0f / 128.0f) + RMS_EPS) * one_m_li;
;             bf16* orow = AO + qtok * 1024 + hp * 128;
	v_pk_mul_f32 v[58:59], v[132:133], v[186:187]
	v_pk_fma_f32 v[20:21], v[20:21], v[0:1], v[142:143] op_sel_hi:[1,0,1] neg_lo:[0,0,1] neg_hi:[0,0,1]
	v_pk_fma_f32 v[58:59], v[56:57], v[0:1], v[58:59] op_sel_hi:[1,0,1] neg_lo:[0,0,1] neg_hi:[0,0,1]
	v_pk_mul_f32 v[56:57], v[132:133], v[194:195]
	v_pk_fma_f32 v[26:27], v[26:27], v[0:1], v[150:151] op_sel_hi:[1,0,1] neg_lo:[0,0,1] neg_hi:[0,0,1]
	v_pk_fma_f32 v[56:57], v[62:63], v[0:1], v[56:57] op_sel_hi:[1,0,1] neg_lo:[0,0,1] neg_hi:[0,0,1]
	v_pk_mul_f32 v[62:63], v[132:133], v[192:193]
	v_pk_fma_f32 v[24:25], v[24:25], v[0:1], v[140:141] op_sel_hi:[1,0,1] neg_lo:[0,0,1] neg_hi:[0,0,1]
	v_pk_fma_f32 v[60:61], v[60:61], v[0:1], v[62:63] op_sel_hi:[1,0,1] neg_lo:[0,0,1] neg_hi:[0,0,1]
	v_pk_mul_f32 v[62:63], v[132:133], v[198:199]
	v_pk_mul_f32 v[198:199], v[132:133], v[200:201]
	v_pk_fma_f32 v[34:35], v[34:35], v[0:1], v[62:63] op_sel_hi:[1,0,1] neg_lo:[0,0,1] neg_hi:[0,0,1]
	v_pk_mul_f32 v[62:63], v[132:133], v[196:197]
	v_pk_mul_f32 v[200:201], v[132:133], v[204:205]
	v_pk_fma_f32 v[62:63], v[32:33], v[0:1], v[62:63] op_sel_hi:[1,0,1] neg_lo:[0,0,1] neg_hi:[0,0,1]
	v_pk_mul_f32 v[32:33], v[132:133], v[202:203]
	v_pk_fma_f32 v[36:37], v[36:37], v[0:1], v[198:199] op_sel_hi:[1,0,1] neg_lo:[0,0,1] neg_hi:[0,0,1]
	v_pk_fma_f32 v[32:33], v[38:39], v[0:1], v[32:33] op_sel_hi:[1,0,1] neg_lo:[0,0,1] neg_hi:[0,0,1]
	v_pk_fma_f32 v[42:43], v[42:43], v[0:1], v[200:201] op_sel_hi:[1,0,1] neg_lo:[0,0,1] neg_hi:[0,0,1]
	v_add_f32_e32 v0, v154, v155
	v_add_f32_e32 v0, v0, v172
	v_pk_mul_f32 v[158:159], v[70:71], v[70:71]
	v_add_f32_e32 v0, v0, v173
	v_add_f32_e32 v0, v0, v158
	v_pk_mul_f32 v[156:157], v[66:67], v[66:67]
	v_add_f32_e32 v0, v0, v159
	v_add_f32_e32 v0, v0, v156
	v_pk_mul_f32 v[162:163], v[74:75], v[74:75]
	v_add_f32_e32 v0, v0, v157
	v_add_f32_e32 v0, v0, v162
	v_pk_mul_f32 v[160:161], v[68:69], v[68:69]
	v_add_f32_e32 v0, v0, v163
	v_add_f32_e32 v0, v0, v160
	v_pk_mul_f32 v[174:175], v[76:77], v[76:77]
	v_add_f32_e32 v0, v0, v161
	v_add_f32_e32 v0, v0, v174
	v_pk_mul_f32 v[164:165], v[72:73], v[72:73]
	v_add_f32_e32 v0, v0, v175
	v_add_f32_e32 v0, v0, v164
	v_pk_mul_f32 v[178:179], v[78:79], v[78:79]
	v_add_f32_e32 v0, v0, v165
	v_add_f32_e32 v0, v0, v178
	v_pk_mul_f32 v[176:177], v[50:51], v[50:51]
	v_add_f32_e32 v0, v0, v179
	v_add_f32_e32 v0, v0, v176
	v_pk_mul_f32 v[182:183], v[54:55], v[54:55]
	v_add_f32_e32 v0, v0, v177
	v_add_f32_e32 v0, v0, v182
	v_pk_mul_f32 v[180:181], v[48:49], v[48:49]
	v_add_f32_e32 v0, v0, v183
	v_add_f32_e32 v0, v0, v180
	v_pk_mul_f32 v[186:187], v[58:59], v[58:59]
	v_add_f32_e32 v0, v0, v181
	v_add_f32_e32 v0, v0, v186
	v_pk_mul_f32 v[184:185], v[52:53], v[52:53]
	v_add_f32_e32 v0, v0, v187
	v_add_f32_e32 v0, v0, v184
	v_pk_mul_f32 v[192:193], v[60:61], v[60:61]
	v_add_f32_e32 v0, v0, v185
	v_add_f32_e32 v0, v0, v192
	v_pk_mul_f32 v[188:189], v[56:57], v[56:57]
	v_add_f32_e32 v0, v0, v193
	v_add_f32_e32 v0, v0, v188
	v_pk_mul_f32 v[196:197], v[62:63], v[62:63]
	v_add_f32_e32 v0, v0, v189
	v_add_f32_e32 v0, v0, v196
	v_pk_mul_f32 v[194:195], v[34:35], v[34:35]
	v_add_f32_e32 v0, v0, v197
	v_add_f32_e32 v0, v0, v194
	v_pk_mul_f32 v[198:199], v[36:37], v[36:37]
	v_add_f32_e32 v0, v0, v195
	v_add_f32_e32 v0, v0, v198
	v_pk_mul_f32 v[38:39], v[32:33], v[32:33]
	v_add_f32_e32 v0, v0, v199
	v_add_f32_e32 v0, v0, v38
	v_pk_mul_f32 v[170:171], v[40:41], v[40:41]
	v_add_f32_e32 v0, v0, v39
	v_add_f32_e32 v0, v0, v170
	v_pk_mul_f32 v[200:201], v[42:43], v[42:43]
	v_add_f32_e32 v0, v0, v171
	v_add_f32_e32 v0, v0, v200
	v_pk_mul_f32 v[166:167], v[44:45], v[44:45]
	v_add_f32_e32 v0, v0, v201
	v_add_f32_e32 v0, v0, v166
	v_pk_mul_f32 v[168:169], v[46:47], v[46:47]
	v_add_f32_e32 v0, v0, v167
	v_add_f32_e32 v0, v0, v168
	v_pk_mul_f32 v[148:149], v[16:17], v[16:17]
	v_add_f32_e32 v0, v0, v169
	v_add_f32_e32 v0, v0, v148
	v_pk_mul_f32 v[152:153], v[18:19], v[18:19]
	v_add_f32_e32 v0, v0, v149
	v_add_f32_e32 v0, v0, v152
	v_pk_mul_f32 v[142:143], v[20:21], v[20:21]
	v_add_f32_e32 v0, v0, v153
	v_add_f32_e32 v0, v0, v142
	v_pk_mul_f32 v[144:145], v[22:23], v[22:23]
	v_add_f32_e32 v0, v0, v143
	v_add_f32_e32 v0, v0, v144
	v_pk_mul_f32 v[140:141], v[24:25], v[24:25]
	v_add_f32_e32 v0, v0, v145
	v_add_f32_e32 v0, v0, v140
	v_pk_mul_f32 v[150:151], v[26:27], v[26:27]
	v_add_f32_e32 v0, v0, v141
	v_add_f32_e32 v0, v0, v150
	v_pk_mul_f32 v[136:137], v[14:15], v[14:15]
	v_add_f32_e32 v0, v0, v151
	v_add_f32_e32 v0, v0, v136
	v_pk_mul_f32 v[138:139], v[28:29], v[28:29]
	v_add_f32_e32 v0, v0, v137
	v_add_f32_e32 v0, v0, v138
	v_add_f32_e32 v0, v0, v139
	ds_bpermute_b32 v136, v191, v0
	v_lshlrev_b64 v[38:39], 11, v[134:135]
	v_lshl_add_u64 v[38:39], s[76:77], 0, v[38:39]
	s_lshl_b32 s80, s18, 1
	v_lshl_add_u64 v[38:39], v[38:39], 0, s[80:81]
	s_waitcnt lgkmcnt(0)
	v_add_f32_e32 v0, v0, v136
	v_fmamk_f32 v0, v0, 0x3c000000, v207
	v_mul_f32_e32 v134, 0x4b800000, v0
	v_cmp_gt_f32_e32 vcc, s87, v0
	s_nop 1
	v_cndmask_b32_e32 v0, v0, v134, vcc
	v_rsq_f32_e32 v134, v0
	v_lshlrev_b32_e32 v0, 2, v190
	v_lshl_add_u64 v[38:39], v[38:39], 0, v[0:1]
	v_mul_f32_e32 v0, 0x45800000, v134
	v_cndmask_b32_e32 v0, v134, v0, vcc
	v_mul_f32_e32 v0, v216, v0
	v_pk_mul_f32 v[64:65], v[64:65], v[0:1] op_sel_hi:[1,0]
	v_pk_mul_f32 v[30:31], v[30:31], v[0:1] op_sel_hi:[1,0]
	s_waitcnt vmcnt(15)
; __device__ __forceinline__ unsigned cvt_pk_bf16(float lo, float hi) { f32x2_t v = {lo, hi}; bf16x2_t b = __builtin_convertvector(v, bf16x2_t); return __builtin_bit_cast(unsigned, b); }
; template <int MODE> ...
;     ...
;             bf16* orow = AO + qtok * 1024 + hp * 128;
; #pragma unroll
;             for (int dvb = 0; dvb < NDV; ++dvb)
; #pragma unroll
;                 for (int g4 = 0; g4 < 4; ++g4) { const int dv0 = 32 * dvb + 8 * g4 + 4 * hi; const f32x4 sg = sgv[dvb][g4];
;                     u32x2 w; w.x = cvt_pk_bf16(acc[dvb][4 * g4 + 0] * rs * sg[0], acc[dvb][4 * g4 + 1] * rs * sg[1]); w.y = cvt_pk_bf16(acc[dvb][4 * g4 + 2] * rs * sg[2], acc[dvb][4 * g4 + 3] * rs * sg[3]);
;                     *(u32x2*)(orow + dv0) = w; }
	v_pk_mul_f32 v[64:65], v[128:129], v[64:65]
	v_pk_mul_f32 v[30:31], v[130:131], v[30:31]
	v_cvt_pk_bf16_f32 v218, v64, v65
	v_cvt_pk_bf16_f32 v219, v30, v31
	v_pk_mul_f32 v[30:31], v[70:71], v[0:1] op_sel_hi:[1,0]
	v_pk_mul_f32 v[64:65], v[66:67], v[0:1] op_sel_hi:[1,0]
	s_waitcnt vmcnt(0)
	v_pk_mul_f32 v[30:31], v[124:125], v[30:31]
	v_pk_mul_f32 v[64:65], v[126:127], v[64:65]
	v_cvt_pk_bf16_f32 v220, v30, v31
	v_cvt_pk_bf16_f32 v221, v64, v65
	s_nop 1
	v_permlane32_swap_b32_e32 v218, v220
	v_permlane32_swap_b32_e32 v219, v221
	global_store_dwordx4 v[38:39], v[218:221], off
	v_pk_mul_f32 v[30:31], v[74:75], v[0:1] op_sel_hi:[1,0]
	v_pk_mul_f32 v[64:65], v[68:69], v[0:1] op_sel_hi:[1,0]
	v_pk_mul_f32 v[30:31], v[120:121], v[30:31]
	v_pk_mul_f32 v[64:65], v[122:123], v[64:65]
	v_cvt_pk_bf16_f32 v222, v30, v31
	v_cvt_pk_bf16_f32 v223, v64, v65
	v_pk_mul_f32 v[30:31], v[76:77], v[0:1] op_sel_hi:[1,0]
	v_pk_mul_f32 v[64:65], v[72:73], v[0:1] op_sel_hi:[1,0]
	v_pk_mul_f32 v[30:31], v[116:117], v[30:31]
	v_pk_mul_f32 v[64:65], v[118:119], v[64:65]
	v_cvt_pk_bf16_f32 v224, v30, v31
	v_cvt_pk_bf16_f32 v225, v64, v65
	s_nop 1
	v_permlane32_swap_b32_e32 v222, v224
	v_permlane32_swap_b32_e32 v223, v225
	global_store_dwordx4 v[38:39], v[222:225], off offset:32
	v_pk_mul_f32 v[30:31], v[78:79], v[0:1] op_sel_hi:[1,0]
	v_pk_mul_f32 v[50:51], v[50:51], v[0:1] op_sel_hi:[1,0]
	v_pk_mul_f32 v[30:31], v[112:113], v[30:31]
	v_pk_mul_f32 v[50:51], v[114:115], v[50:51]
	v_cvt_pk_bf16_f32 v242, v30, v31
	v_cvt_pk_bf16_f32 v243, v50, v51
	v_pk_mul_f32 v[30:31], v[54:55], v[0:1] op_sel_hi:[1,0]
	v_pk_mul_f32 v[48:49], v[48:49], v[0:1] op_sel_hi:[1,0]
	v_pk_mul_f32 v[30:31], v[108:109], v[30:31]
	v_pk_mul_f32 v[48:49], v[110:111], v[48:49]
	v_cvt_pk_bf16_f32 v244, v30, v31
	v_cvt_pk_bf16_f32 v245, v48, v49
	s_nop 1
	v_permlane32_swap_b32_e32 v242, v244
	v_permlane32_swap_b32_e32 v243, v245
	global_store_dwordx4 v[38:39], v[242:245], off offset:64
	v_pk_mul_f32 v[30:31], v[58:59], v[0:1] op_sel_hi:[1,0]
	v_pk_mul_f32 v[48:49], v[52:53], v[0:1] op_sel_hi:[1,0]
	v_pk_mul_f32 v[30:31], v[104:105], v[30:31]
	v_pk_mul_f32 v[48:49], v[106:107], v[48:49]
	v_cvt_pk_bf16_f32 v246, v30, v31
	v_cvt_pk_bf16_f32 v247, v48, v49
	v_pk_mul_f32 v[30:31], v[60:61], v[0:1] op_sel_hi:[1,0]
	v_pk_mul_f32 v[48:49], v[56:57], v[0:1] op_sel_hi:[1,0]
	v_pk_mul_f32 v[16:17], v[16:17], v[0:1] op_sel_hi:[1,0]
	v_pk_mul_f32 v[18:19], v[18:19], v[0:1] op_sel_hi:[1,0]
	v_pk_mul_f32 v[30:31], v[100:101], v[30:31]
	v_pk_mul_f32 v[48:49], v[102:103], v[48:49]
	v_pk_mul_f32 v[16:17], v[80:81], v[16:17]
	v_pk_mul_f32 v[18:19], v[82:83], v[18:19]
	v_cvt_pk_bf16_f32 v248, v30, v31
	v_cvt_pk_bf16_f32 v249, v48, v49
	v_cvt_pk_bf16_f32 v242, v16, v17
	v_cvt_pk_bf16_f32 v243, v18, v19
	s_nop 1
	v_permlane32_swap_b32_e32 v246, v248
	v_permlane32_swap_b32_e32 v247, v249
	global_store_dwordx4 v[38:39], v[246:249], off offset:96
	v_pk_mul_f32 v[30:31], v[62:63], v[0:1] op_sel_hi:[1,0]
	v_pk_mul_f32 v[34:35], v[34:35], v[0:1] op_sel_hi:[1,0]
	v_pk_mul_f32 v[16:17], v[20:21], v[0:1] op_sel_hi:[1,0]
	v_pk_mul_f32 v[30:31], v[96:97], v[30:31]
	v_pk_mul_f32 v[34:35], v[98:99], v[34:35]
	v_pk_mul_f32 v[10:11], v[10:11], v[16:17]
	v_pk_mul_f32 v[16:17], v[22:23], v[0:1] op_sel_hi:[1,0]
	v_cvt_pk_bf16_f32 v218, v30, v31
	v_cvt_pk_bf16_f32 v219, v34, v35
	v_pk_mul_f32 v[12:13], v[12:13], v[16:17]
	v_pk_mul_f32 v[30:31], v[36:37], v[0:1] op_sel_hi:[1,0]
	v_pk_mul_f32 v[32:33], v[32:33], v[0:1] op_sel_hi:[1,0]
	v_cvt_pk_bf16_f32 v244, v10, v11
	v_cvt_pk_bf16_f32 v245, v12, v13
	v_pk_mul_f32 v[30:31], v[92:93], v[30:31]
	v_pk_mul_f32 v[32:33], v[94:95], v[32:33]
	s_nop 1
	v_permlane32_swap_b32_e32 v242, v244
	v_permlane32_swap_b32_e32 v243, v245
	global_store_dwordx4 v[38:39], v[242:245], off offset:192
	v_pk_mul_f32 v[10:11], v[24:25], v[0:1] op_sel_hi:[1,0]
	v_cvt_pk_bf16_f32 v220, v30, v31
	v_cvt_pk_bf16_f32 v221, v32, v33
	v_pk_mul_f32 v[6:7], v[6:7], v[10:11]
	v_pk_mul_f32 v[10:11], v[26:27], v[0:1] op_sel_hi:[1,0]
	s_nop 1
	v_permlane32_swap_b32_e32 v218, v220
	v_permlane32_swap_b32_e32 v219, v221
	global_store_dwordx4 v[38:39], v[218:221], off offset:128
	v_pk_mul_f32 v[30:31], v[40:41], v[0:1] op_sel_hi:[1,0]
	v_pk_mul_f32 v[32:33], v[42:43], v[0:1] op_sel_hi:[1,0]
	v_pk_mul_f32 v[8:9], v[8:9], v[10:11]
	v_pk_mul_f32 v[30:31], v[88:89], v[30:31]
	v_pk_mul_f32 v[32:33], v[90:91], v[32:33]
	v_cvt_pk_bf16_f32 v246, v6, v7
	v_cvt_pk_bf16_f32 v247, v8, v9
	v_cvt_pk_bf16_f32 v222, v30, v31
	v_cvt_pk_bf16_f32 v223, v32, v33
	v_pk_mul_f32 v[6:7], v[14:15], v[0:1] op_sel_hi:[1,0]
	v_pk_mul_f32 v[30:31], v[44:45], v[0:1] op_sel_hi:[1,0]
	v_pk_mul_f32 v[32:33], v[46:47], v[0:1] op_sel_hi:[1,0]
	v_pk_mul_f32 v[2:3], v[2:3], v[6:7]
	v_pk_mul_f32 v[6:7], v[28:29], v[0:1] op_sel_hi:[1,0]
	v_pk_mul_f32 v[30:31], v[84:85], v[30:31]
	v_pk_mul_f32 v[32:33], v[86:87], v[32:33]
	v_pk_mul_f32 v[4:5], v[4:5], v[6:7]
	v_cvt_pk_bf16_f32 v224, v30, v31
	v_cvt_pk_bf16_f32 v225, v32, v33
	v_cvt_pk_bf16_f32 v248, v2, v3
	v_cvt_pk_bf16_f32 v249, v4, v5
	s_nop 1
	v_permlane32_swap_b32_e32 v222, v224
	v_permlane32_swap_b32_e32 v223, v225
	global_store_dwordx4 v[38:39], v[222:225], off offset:160
	s_nop 1
	v_permlane32_swap_b32_e32 v246, v248
	v_permlane32_swap_b32_e32 v247, v249
	global_store_dwordx4 v[38:39], v[246:249], off offset:224
	s_branch .LBB0_377

; __device__ __forceinline__ unsigned cvt_pk_bf16(float lo, float hi) { f32x2_t v = {lo, hi}; bf16x2_t b = __builtin_convertvector(v, bf16x2_t); return __builtin_bit_cast(unsigned, b); }
; __device__ __forceinline__ float bflo(unsigned w) { return __uint_as_float(w << 16); }
; __device__ __forceinline__ float bfhi(unsigned w) { return __uint_as_float(w & 0xffff0000u); }
; template <int MODE> ...
;     ...
;         const float sc = inv * wg;
;         bf16* orow = AO + qtok * 1024 + head * 64;
; #pragma unroll
;         for (int dvb = 0; dvb < NDV; ++dvb)
; #pragma unroll
;             for (int g4 = 0; g4 < 4; ++g4) { const int dv0 = 32 * dvb + 8 * g4 + 4 * hi;
;                 float o0 = acc[dvb][4 * g4 + 0] * sc, o1 = acc[dvb][4 * g4 + 1] * sc, o2 = acc[dvb][4 * g4 + 2] * sc, o3 = acc[dvb][4 * g4 + 3] * sc;
;                 if (gidx > 0) { const u32x2 pw = pw_pre[dvb][g4]; o0 += wa * bflo(pw.x); o1 += wa * bfhi(pw.x); o2 += wa * bflo(pw.y); o3 += wa * bfhi(pw.y); }
;                 u32x2 w; w.x = cvt_pk_bf16(o0, o1); w.y = cvt_pk_bf16(o2, o3);
;                 *(u32x2*)(orow + dv0) = w; }
;         if (hi == 0 && gidx < 2) LSE[qtok * 16 + head] = lsen;
.LBB0_450:
	s_add_i32 s10, s10, s27
	s_lshl_b32 s12, s10, 6
	s_ashr_i32 s13, s12, 31
	v_mov_b32_e32 v35, v34
	v_lshl_add_u64 v[38:39], s[12:13], 1, v[116:117]
	s_waitcnt vmcnt(0) lgkmcnt(0)
	v_mov_b32_e32 v113, v1
	v_cvt_pk_bf16_f32 v218, v18, v19
	v_cvt_pk_bf16_f32 v219, v20, v21
	v_lshlrev_b32_e32 v226, 4, v178
	v_mov_b32_e32 v227, v1
	v_lshl_add_u64 v[18:19], v[38:39], 0, v[226:227]
	v_pk_mul_f32 v[20:21], v[22:23], v[34:35]
	s_and_b64 vcc, exec, s[0:1]
	v_pk_mul_f32 v[22:23], v[24:25], v[34:35]
	s_cbranch_vccnz .LBB0_452
	v_lshlrev_b32_e32 v24, 16, v114
	v_and_b32_e32 v25, 0xffff0000, v114
	v_pk_fma_f32 v[20:21], v[0:1], v[24:25], v[20:21] op_sel_hi:[0,1,1]
	v_lshlrev_b32_e32 v24, 16, v115
	v_and_b32_e32 v25, 0xffff0000, v115
	v_pk_fma_f32 v[22:23], v[0:1], v[24:25], v[22:23] op_sel_hi:[0,1,1]
.LBB0_452:
	v_cvt_pk_bf16_f32 v220, v20, v21
	v_cvt_pk_bf16_f32 v221, v22, v23
	s_nop 1
	v_permlane32_swap_b32_e32 v218, v220
	v_permlane32_swap_b32_e32 v219, v221
	global_store_dwordx4 v[18:19], v[218:221], off
	v_pk_mul_f32 v[20:21], v[26:27], v[34:35]
	s_and_b64 vcc, exec, s[0:1]
	v_pk_mul_f32 v[22:23], v[28:29], v[34:35]
	s_cbranch_vccnz .LBB0_454
	v_lshlrev_b32_e32 v24, 16, v110
	v_and_b32_e32 v25, 0xffff0000, v110
	v_pk_fma_f32 v[20:21], v[0:1], v[24:25], v[20:21] op_sel_hi:[0,1,1]
	v_lshlrev_b32_e32 v24, 16, v111
	v_and_b32_e32 v25, 0xffff0000, v111
	v_pk_fma_f32 v[22:23], v[0:1], v[24:25], v[22:23] op_sel_hi:[0,1,1]
.LBB0_454:
	v_cvt_pk_bf16_f32 v222, v20, v21
	v_cvt_pk_bf16_f32 v223, v22, v23
	v_pk_mul_f32 v[20:21], v[30:31], v[34:35]
	s_and_b64 vcc, exec, s[0:1]
	v_pk_mul_f32 v[22:23], v[32:33], v[34:35]
	s_cbranch_vccnz .LBB0_456
	v_lshlrev_b32_e32 v24, 16, v108
	v_and_b32_e32 v25, 0xffff0000, v108
	v_pk_fma_f32 v[20:21], v[0:1], v[24:25], v[20:21] op_sel_hi:[0,1,1]
	v_lshlrev_b32_e32 v24, 16, v109
	v_and_b32_e32 v25, 0xffff0000, v109
	v_pk_fma_f32 v[22:23], v[0:1], v[24:25], v[22:23] op_sel_hi:[0,1,1]
.LBB0_456:
	v_cvt_pk_bf16_f32 v224, v20, v21
	v_cvt_pk_bf16_f32 v225, v22, v23
	v_pk_mul_f32 v[2:3], v[2:3], v[34:35]
	s_and_b64 vcc, exec, s[0:1]
	v_pk_mul_f32 v[4:5], v[4:5], v[34:35]
	s_nop 1
	v_permlane32_swap_b32_e32 v222, v224
	v_permlane32_swap_b32_e32 v223, v225
	global_store_dwordx4 v[18:19], v[222:225], off offset:32
	s_cbranch_vccnz .LBB0_458
	v_lshlrev_b32_e32 v20, 16, v106
	v_and_b32_e32 v21, 0xffff0000, v106
	v_pk_fma_f32 v[2:3], v[0:1], v[20:21], v[2:3] op_sel_hi:[0,1,1]
	v_lshlrev_b32_e32 v20, 16, v107
	v_and_b32_e32 v21, 0xffff0000, v107
	v_pk_fma_f32 v[4:5], v[0:1], v[20:21], v[4:5] op_sel_hi:[0,1,1]
.LBB0_458:
	v_cvt_pk_bf16_f32 v242, v2, v3
	v_cvt_pk_bf16_f32 v243, v4, v5
	v_pk_mul_f32 v[2:3], v[6:7], v[34:35]
	s_and_b64 vcc, exec, s[0:1]
	v_pk_mul_f32 v[4:5], v[8:9], v[34:35]
	s_cbranch_vccnz .LBB0_460
	v_lshlrev_b32_e32 v6, 16, v104
	v_and_b32_e32 v7, 0xffff0000, v104
	v_pk_fma_f32 v[2:3], v[0:1], v[6:7], v[2:3] op_sel_hi:[0,1,1]
	v_lshlrev_b32_e32 v6, 16, v105
	v_and_b32_e32 v7, 0xffff0000, v105
	v_pk_fma_f32 v[4:5], v[0:1], v[6:7], v[4:5] op_sel_hi:[0,1,1]
.LBB0_460:
	v_cvt_pk_bf16_f32 v244, v2, v3
	v_cvt_pk_bf16_f32 v245, v4, v5
	s_nop 1
	v_permlane32_swap_b32_e32 v242, v244
	v_permlane32_swap_b32_e32 v243, v245
	global_store_dwordx4 v[18:19], v[242:245], off offset:64
	v_pk_mul_f32 v[2:3], v[10:11], v[34:35]
	s_and_b64 vcc, exec, s[0:1]
	v_pk_mul_f32 v[4:5], v[12:13], v[34:35]
	s_cbranch_vccnz .LBB0_462
	v_lshlrev_b32_e32 v6, 16, v102
	v_and_b32_e32 v7, 0xffff0000, v102
	v_pk_fma_f32 v[2:3], v[0:1], v[6:7], v[2:3] op_sel_hi:[0,1,1]
	v_lshlrev_b32_e32 v6, 16, v103
	v_and_b32_e32 v7, 0xffff0000, v103
	v_pk_fma_f32 v[4:5], v[0:1], v[6:7], v[4:5] op_sel_hi:[0,1,1]
.LBB0_462:
	v_cvt_pk_bf16_f32 v246, v2, v3
	v_cvt_pk_bf16_f32 v247, v4, v5
	v_pk_mul_f32 v[2:3], v[14:15], v[34:35]
	s_and_b64 vcc, exec, s[0:1]
	v_pk_mul_f32 v[4:5], v[16:17], v[34:35]
	s_cbranch_vccnz .LBB0_464
	v_lshlrev_b32_e32 v6, 16, v100
	v_and_b32_e32 v7, 0xffff0000, v100
	v_pk_fma_f32 v[2:3], v[0:1], v[6:7], v[2:3] op_sel_hi:[0,1,1]
	v_lshlrev_b32_e32 v6, 16, v101
	v_and_b32_e32 v7, 0xffff0000, v101
	v_pk_fma_f32 v[4:5], v[0:1], v[6:7], v[4:5] op_sel_hi:[0,1,1]
.LBB0_464:
	v_cmp_eq_u32_e32 vcc, 0, v178
	v_cvt_pk_bf16_f32 v248, v2, v3
	v_cvt_pk_bf16_f32 v249, v4, v5
	s_and_b64 s[12:13], s[8:9], vcc
	s_nop 1
	v_permlane32_swap_b32_e32 v246, v248
	v_permlane32_swap_b32_e32 v247, v249
	global_store_dwordx4 v[18:19], v[246:249], off offset:96
	s_and_saveexec_b64 s[0:1], s[12:13]
	s_cbranch_execz .LBB0_426
	s_ashr_i32 s11, s10, 31
	v_lshl_add_u64 v[2:3], s[10:11], 2, v[98:99]
	flat_store_dword v[2:3], v36
	s_branch .LBB0_426
